# GEMM prologues: K-tile 1's six LDS-DMAs issued right behind K-tile 0's eight (first wait vmcnt(2) -> vmcnt(8) behind them), so the first K-loop iterations do not wait a second memory latency
# speedup vs baseline: 1.0072x; 1.0072x over previous
.LBB0_239:
	s_lshl_b32 s5, s5, 5
	s_mov_b64 s[40:41], 0x80
	s_and_b32 s5, s5, 0x60
	s_add_i32 m0, s27, 0x18000
	v_lshl_add_u64 v[8:9], v[8:9], 0, s[40:41]
	s_lshl_b32 s7, s4, 13
	s_lshl_b32 s44, s5, 7
	global_load_lds_dwordx4 v[8:9], off
	v_lshl_add_u64 v[6:7], v[6:7], 0, s[40:41]
	s_add_i32 m0, s27, 0x1a000
	s_add_i32 s87, s27, 0x8000
	s_add_i32 s88, s27, 0xa000
	global_load_lds_dwordx4 v[6:7], off
	v_lshl_add_u64 v[2:3], v[2:3], 0, s[40:41]
	s_mov_b32 m0, s87
	s_add_u32 s42, s82, 0x40080
	global_load_lds_dwordx4 v[2:3], off
	v_lshl_add_u64 v[2:3], v[4:5], 0, s[40:41]
	s_mov_b32 m0, s88
	s_addc_u32 s43, s83, 0
	global_load_lds_dwordx4 v[2:3], off
	s_add_i32 m0, s27, 0x1c000
	v_lshl_add_u64 v[2:3], s[42:43], 0, v[140:141]
	global_load_lds_dwordx4 v[2:3], off
	v_lshl_add_u64 v[2:3], s[42:43], 0, v[144:145]
	s_add_i32 m0, s27, 0x1e000
	v_lshlrev_b32_e32 v4, 2, v0
	global_load_lds_dwordx4 v[2:3], off
	s_waitcnt vmcnt(8)
	s_barrier
	v_and_b32_e32 v2, 15, v0
	v_lshl_or_b32 v159, s4, 6, v2
	v_lshlrev_b32_e32 v3, 1, v14
	s_movk_i32 s4, 0x3c0
	v_lshl_or_b32 v2, v2, 6, v3
	v_and_b32_e32 v4, 32, v4
	v_and_or_b32 v3, v158, s4, v3
	v_bitop3_b32 v160, s44, v3, v4 bitop3:0xf6
	v_lshlrev_b32_e32 v3, 8, v0
	v_bitop3_b32 v2, v2, s7, v4 bitop3:0xde
	v_and_b32_e32 v3, 0x18000, v3
	v_lshlrev_b32_e32 v4, 11, v12
	v_or3_b32 v3, v10, v3, v4
	v_add_u32_e32 v150, v3, v11
	v_lshlrev_b32_e32 v3, 4, v13
	s_waitcnt vmcnt(6)
	s_cmpk_lt_u32 s0, 0x100
	v_and_b32_e32 v3, 0x38000, v3
	s_cselect_b64 s[42:43], -1, 0
	v_or3_b32 v3, v10, v3, v4
	s_add_i32 s90, 0, 0x10000
	s_add_i32 s91, 0, 0x14000
	v_or_b32_e32 v148, s5, v14
	s_ashr_i32 s89, s33, 31
	v_mov_b32_e32 v151, v147
	v_add_u32_e32 v152, v3, v11
	v_mov_b32_e32 v153, v147
	v_mov_b64_e32 v[154:155], 0x280
	v_mov_b64_e32 v[156:157], 0x27f
	s_mov_b64 s[44:45], 0x100
	v_add_u32_e32 v161, s90, v160
	v_add_u32_e32 v162, s91, v160
	v_add_u32_e32 v163, 0, v2
	s_movk_i32 s92, 0xc00
	s_barrier
	s_branch .LBB0_242

.LBB0_559:
	s_mov_b64 s[12:13], 0x80
	s_and_b32 s15, s48, 3
	s_add_i32 m0, s17, 0x18000
	v_lshl_add_u64 v[8:9], v[8:9], 0, s[12:13]
	s_lshl_b32 s61, s1, 6
	s_lshl_b32 s0, s1, 13
	s_lshl_b32 s8, s15, 12
	global_load_lds_dwordx4 v[8:9], off
	v_lshl_add_u64 v[6:7], v[6:7], 0, s[12:13]
	s_add_i32 m0, s17, 0x1a000
	s_add_i32 s68, s17, 0x8000
	s_add_i32 s69, s17, 0xa000
	global_load_lds_dwordx4 v[6:7], off
	v_lshl_add_u64 v[4:5], v[4:5], 0, s[12:13]
	s_mov_b32 m0, s68
	s_add_u32 s6, s40, 0x40080
	global_load_lds_dwordx4 v[4:5], off
	v_lshl_add_u64 v[2:3], v[2:3], 0, s[12:13]
	s_mov_b32 m0, s69
	s_addc_u32 s7, s41, 0
	global_load_lds_dwordx4 v[2:3], off
	s_add_i32 m0, s17, 0x1c000
	v_lshl_add_u64 v[2:3], s[6:7], 0, v[132:133]
	global_load_lds_dwordx4 v[2:3], off
	v_lshl_add_u64 v[2:3], s[6:7], 0, v[136:137]
	s_add_i32 m0, s17, 0x1e000
	v_and_b32_e32 v219, 15, v0
	global_load_lds_dwordx4 v[2:3], off
	s_waitcnt vmcnt(8)
	s_barrier
	v_and_b32_e32 v2, 48, v0
	v_lshlrev_b32_e32 v4, 2, v0
	v_lshl_or_b32 v3, v219, 6, v2
	v_and_b32_e32 v4, 32, v4
	v_bitop3_b32 v6, v3, s0, v4 bitop3:0xde
	v_lshlrev_b32_e32 v3, 6, v0
	s_movk_i32 s0, 0x3c0
	v_and_or_b32 v2, v3, s0, v2
	v_bitop3_b32 v151, s8, v2, v4 bitop3:0xf6
	v_lshlrev_b32_e32 v2, 8, v0
	v_and_b32_e32 v2, 0x18000, v2
	v_lshlrev_b32_e32 v4, 11, v12
	v_or3_b32 v2, v10, v2, v4
	s_mov_b64 s[6:7], 0x40080
	v_add_u32_e32 v2, v2, v11
	v_mov_b32_e32 v3, v133
	v_lshl_add_u64 v[138:139], v[2:3], 0, s[6:7]
	v_lshlrev_b32_e32 v2, 4, v13
	v_and_b32_e32 v2, 0x38000, v2
	v_or3_b32 v2, v10, v2, v4
	s_waitcnt vmcnt(6)
	v_add_u32_e32 v2, v2, v11
	v_mov_b32_e32 v4, v133
	v_mov_b32_e32 v5, v133
	v_lshl_add_u64 v[140:141], v[2:3], 0, s[6:7]
	v_mov_b32_e32 v2, v133
	v_add_u32_e32 v152, 0, v6
	v_mov_b64_e32 v[8:9], v[4:5]
	v_mov_b64_e32 v[20:21], v[4:5]
	v_mov_b64_e32 v[24:25], v[4:5]
	v_mov_b64_e32 v[36:37], v[4:5]
	v_mov_b64_e32 v[40:41], v[4:5]
	v_mov_b64_e32 v[52:53], v[4:5]
	v_mov_b64_e32 v[56:57], v[4:5]
	v_mov_b64_e32 v[12:13], v[4:5]
	v_mov_b64_e32 v[16:17], v[4:5]
	v_mov_b64_e32 v[28:29], v[4:5]
	v_mov_b64_e32 v[32:33], v[4:5]
	v_mov_b64_e32 v[44:45], v[4:5]
	v_mov_b64_e32 v[48:49], v[4:5]
	v_mov_b64_e32 v[60:61], v[4:5]
	v_mov_b64_e32 v[64:65], v[4:5]
	v_mov_b64_e32 v[68:69], v[4:5]
	v_mov_b64_e32 v[72:73], v[4:5]
	v_mov_b64_e32 v[84:85], v[4:5]
	v_mov_b64_e32 v[88:89], v[4:5]
	v_mov_b64_e32 v[100:101], v[4:5]
	v_mov_b64_e32 v[104:105], v[4:5]
	v_mov_b64_e32 v[116:117], v[4:5]
	v_mov_b64_e32 v[120:121], v[4:5]
	v_mov_b64_e32 v[76:77], v[4:5]
	v_mov_b64_e32 v[80:81], v[4:5]
	v_mov_b64_e32 v[92:93], v[4:5]
	v_mov_b64_e32 v[96:97], v[4:5]
	v_mov_b64_e32 v[108:109], v[4:5]
	v_mov_b64_e32 v[112:113], v[4:5]
	v_mov_b64_e32 v[124:125], v[4:5]
	v_mov_b64_e32 v[128:129], v[4:5]
	v_or_b32_e32 v217, s61, v219
	s_mov_b32 s70, 0
	v_mov_b64_e32 v[142:143], 0x100
	v_mov_b64_e32 v[144:145], 0xff
	s_add_i32 s71, 0, 0x10000
	s_add_i32 s72, 0, 0x14000
	v_mov_b64_e32 v[6:7], v[2:3]
	v_mov_b64_e32 v[18:19], v[2:3]
	v_mov_b64_e32 v[22:23], v[2:3]
	v_mov_b64_e32 v[34:35], v[2:3]
	v_mov_b64_e32 v[38:39], v[2:3]
	v_mov_b64_e32 v[50:51], v[2:3]
	v_mov_b64_e32 v[54:55], v[2:3]
	v_mov_b64_e32 v[10:11], v[2:3]
	v_mov_b64_e32 v[14:15], v[2:3]
	v_mov_b64_e32 v[26:27], v[2:3]
	v_mov_b64_e32 v[30:31], v[2:3]
	v_mov_b64_e32 v[42:43], v[2:3]
	v_mov_b64_e32 v[46:47], v[2:3]
	v_mov_b64_e32 v[58:59], v[2:3]
	v_mov_b64_e32 v[62:63], v[2:3]
	v_mov_b64_e32 v[66:67], v[2:3]
	v_mov_b64_e32 v[70:71], v[2:3]
	v_mov_b64_e32 v[82:83], v[2:3]
	v_mov_b64_e32 v[86:87], v[2:3]
	v_mov_b64_e32 v[98:99], v[2:3]
	v_mov_b64_e32 v[102:103], v[2:3]
	v_mov_b64_e32 v[114:115], v[2:3]
	v_mov_b64_e32 v[118:119], v[2:3]
	v_mov_b64_e32 v[74:75], v[2:3]
	v_mov_b64_e32 v[78:79], v[2:3]
	v_mov_b64_e32 v[90:91], v[2:3]
	v_mov_b64_e32 v[94:95], v[2:3]
	v_mov_b64_e32 v[106:107], v[2:3]
	v_mov_b64_e32 v[110:111], v[2:3]
	v_mov_b64_e32 v[122:123], v[2:3]
	v_mov_b64_e32 v[126:127], v[2:3]
	s_barrier

.LBB0_762:
	s_lshl_b32 s7, s7, 5
	s_mov_b64 s[12:13], 0x80
	s_and_b32 s7, s7, 0x60
	s_add_i32 m0, s29, 0x18000
	v_lshl_add_u64 v[8:9], v[8:9], 0, s[12:13]
	s_lshl_b32 s16, s6, 13
	s_lshl_b32 s17, s7, 7
	global_load_lds_dwordx4 v[8:9], off
	v_lshl_add_u64 v[6:7], v[6:7], 0, s[12:13]
	s_add_i32 m0, s29, 0x1a000
	s_add_i32 s48, s29, 0x8000
	s_add_i32 s49, s29, 0xa000
	global_load_lds_dwordx4 v[6:7], off
	v_lshl_add_u64 v[2:3], v[2:3], 0, s[12:13]
	s_mov_b32 m0, s48
	s_add_u32 s14, s40, 0x40080
	global_load_lds_dwordx4 v[2:3], off
	v_lshl_add_u64 v[2:3], v[4:5], 0, s[12:13]
	s_mov_b32 m0, s49
	s_addc_u32 s15, s41, 0
	global_load_lds_dwordx4 v[2:3], off
	s_add_i32 m0, s29, 0x1c000
	v_lshl_add_u64 v[2:3], s[14:15], 0, v[134:135]
	global_load_lds_dwordx4 v[2:3], off
	v_lshl_add_u64 v[2:3], s[14:15], 0, v[130:131]
	s_add_i32 m0, s29, 0x1e000
	v_lshlrev_b32_e32 v4, 2, v0
	global_load_lds_dwordx4 v[2:3], off
	s_waitcnt vmcnt(8)
	s_barrier
	v_and_b32_e32 v2, 15, v0
	v_lshl_or_b32 v150, s6, 6, v2
	v_lshlrev_b32_e32 v3, 1, v13
	v_lshlrev_b32_e32 v5, 6, v0
	s_movk_i32 s6, 0x3c0
	v_lshl_or_b32 v2, v2, 6, v3
	v_and_b32_e32 v4, 32, v4
	v_and_or_b32 v3, v5, s6, v3
	v_bitop3_b32 v151, s17, v3, v4 bitop3:0xf6
	v_lshlrev_b32_e32 v3, 8, v0
	v_bitop3_b32 v2, v2, s16, v4 bitop3:0xde
	v_and_b32_e32 v3, 0x18000, v3
	v_lshlrev_b32_e32 v4, 11, v14
	v_or3_b32 v3, v11, v3, v4
	v_add_u32_e32 v138, v3, v12
	v_lshlrev_b32_e32 v3, 4, v10
	s_waitcnt vmcnt(6)
	s_cmpk_lt_u32 s0, 0x100
	v_and_b32_e32 v3, 0x38000, v3
	s_cselect_b64 s[14:15], -1, 0
	v_or3_b32 v3, v11, v3, v4
	s_add_i32 s51, 0, 0x10000
	s_add_i32 s60, 0, 0x14000
	s_ashr_i32 s50, s33, 31
	v_or_b32_e32 v152, s7, v13
	v_mov_b32_e32 v139, v135
	v_add_u32_e32 v140, v3, v12
	v_mov_b32_e32 v141, v135
	v_mov_b64_e32 v[142:143], 0x580
	v_mov_b64_e32 v[144:145], 0x57f
	v_add_u32_e32 v153, s51, v151
	v_add_u32_e32 v154, s60, v151
	v_add_u32_e32 v155, 0, v2
	s_movk_i32 s61, 0x1600
	s_barrier
	s_branch .LBB0_765

.LBB0_862:
	s_mov_b64 s[14:15], 0x80
	s_and_b32 s31, s28, 3
	s_add_i32 m0, s37, 0x18000
	v_lshl_add_u64 v[8:9], v[8:9], 0, s[14:15]
	s_lshl_b32 s30, s11, 6
	s_lshl_b32 s4, s11, 13
	s_lshl_b32 s5, s31, 12
	global_load_lds_dwordx4 v[8:9], off
	v_lshl_add_u64 v[6:7], v[6:7], 0, s[14:15]
	s_add_i32 m0, s37, 0x1a000
	s_add_i32 s41, s37, 0x8000
	s_add_i32 s42, s37, 0xa000
	global_load_lds_dwordx4 v[6:7], off
	v_lshl_add_u64 v[4:5], v[4:5], 0, s[14:15]
	s_mov_b32 m0, s41
	s_add_u32 s0, s20, 0xb0080
	global_load_lds_dwordx4 v[4:5], off
	v_lshl_add_u64 v[2:3], v[2:3], 0, s[14:15]
	s_mov_b32 m0, s42
	s_addc_u32 s1, s21, 0
	global_load_lds_dwordx4 v[2:3], off
	s_add_i32 m0, s37, 0x1c000
	v_lshl_add_u64 v[2:3], s[0:1], 0, v[132:133]
	global_load_lds_dwordx4 v[2:3], off
	v_lshl_add_u64 v[2:3], s[0:1], 0, v[136:137]
	s_add_i32 m0, s37, 0x1e000
	v_and_b32_e32 v213, 15, v0
	global_load_lds_dwordx4 v[2:3], off
	s_waitcnt vmcnt(8)
	s_barrier
	v_and_b32_e32 v2, 48, v0
	v_lshlrev_b32_e32 v4, 2, v0
	v_lshl_or_b32 v3, v213, 6, v2
	v_and_b32_e32 v4, 32, v4
	v_bitop3_b32 v6, v3, s4, v4 bitop3:0xde
	v_lshlrev_b32_e32 v3, 6, v0
	s_movk_i32 s0, 0x3c0
	v_and_or_b32 v2, v3, s0, v2
	v_bitop3_b32 v150, s5, v2, v4 bitop3:0xf6
	v_add_u16_e32 v2, v10, v11
	v_lshrrev_b16_e32 v4, 1, v2
	s_mov_b64 s[0:1], 0xb0080
	v_add_lshl_u32 v2, v12, v4, 1
	v_mov_b32_e32 v3, v133
	s_waitcnt vmcnt(6)
	v_lshl_add_u64 v[138:139], v[2:3], 0, s[0:1]
	v_add_lshl_u32 v2, v13, v4, 1
	v_mov_b32_e32 v4, v133
	v_mov_b32_e32 v5, v133
	v_lshl_add_u64 v[140:141], v[2:3], 0, s[0:1]
	v_mov_b32_e32 v2, v133
	v_add_u32_e32 v151, 0, v6
	v_mov_b64_e32 v[8:9], v[4:5]
	v_mov_b64_e32 v[20:21], v[4:5]
	v_mov_b64_e32 v[24:25], v[4:5]
	v_mov_b64_e32 v[36:37], v[4:5]
	v_mov_b64_e32 v[40:41], v[4:5]
	v_mov_b64_e32 v[52:53], v[4:5]
	v_mov_b64_e32 v[56:57], v[4:5]
	v_mov_b64_e32 v[12:13], v[4:5]
	v_mov_b64_e32 v[16:17], v[4:5]
	v_mov_b64_e32 v[28:29], v[4:5]
	v_mov_b64_e32 v[32:33], v[4:5]
	v_mov_b64_e32 v[44:45], v[4:5]
	v_mov_b64_e32 v[48:49], v[4:5]
	v_mov_b64_e32 v[60:61], v[4:5]
	v_mov_b64_e32 v[64:65], v[4:5]
	v_mov_b64_e32 v[68:69], v[4:5]
	v_mov_b64_e32 v[72:73], v[4:5]
	v_mov_b64_e32 v[84:85], v[4:5]
	v_mov_b64_e32 v[88:89], v[4:5]
	v_mov_b64_e32 v[100:101], v[4:5]
	v_mov_b64_e32 v[104:105], v[4:5]
	v_mov_b64_e32 v[116:117], v[4:5]
	v_mov_b64_e32 v[120:121], v[4:5]
	v_mov_b64_e32 v[76:77], v[4:5]
	v_mov_b64_e32 v[80:81], v[4:5]
	v_mov_b64_e32 v[92:93], v[4:5]
	v_mov_b64_e32 v[96:97], v[4:5]
	v_mov_b64_e32 v[108:109], v[4:5]
	v_mov_b64_e32 v[112:113], v[4:5]
	v_mov_b64_e32 v[124:125], v[4:5]
	v_mov_b64_e32 v[128:129], v[4:5]
	s_mov_b32 s43, 0
	v_mov_b64_e32 v[142:143], 0x100
	v_mov_b64_e32 v[144:145], 0xff
	s_add_i32 s44, 0, 0x10000
	s_add_i32 s45, 0, 0x14000
	v_mov_b64_e32 v[6:7], v[2:3]
	v_mov_b64_e32 v[18:19], v[2:3]
	v_mov_b64_e32 v[22:23], v[2:3]
	v_mov_b64_e32 v[34:35], v[2:3]
	v_mov_b64_e32 v[38:39], v[2:3]
	v_mov_b64_e32 v[50:51], v[2:3]
	v_mov_b64_e32 v[54:55], v[2:3]
	v_mov_b64_e32 v[10:11], v[2:3]
	v_mov_b64_e32 v[14:15], v[2:3]
	v_mov_b64_e32 v[26:27], v[2:3]
	v_mov_b64_e32 v[30:31], v[2:3]
	v_mov_b64_e32 v[42:43], v[2:3]
	v_mov_b64_e32 v[46:47], v[2:3]
	v_mov_b64_e32 v[58:59], v[2:3]
	v_mov_b64_e32 v[62:63], v[2:3]
	v_mov_b64_e32 v[66:67], v[2:3]
	v_mov_b64_e32 v[70:71], v[2:3]
	v_mov_b64_e32 v[82:83], v[2:3]
	v_mov_b64_e32 v[86:87], v[2:3]
	v_mov_b64_e32 v[98:99], v[2:3]
	v_mov_b64_e32 v[102:103], v[2:3]
	v_mov_b64_e32 v[114:115], v[2:3]
	v_mov_b64_e32 v[118:119], v[2:3]
	v_mov_b64_e32 v[74:75], v[2:3]
	v_mov_b64_e32 v[78:79], v[2:3]
	v_mov_b64_e32 v[90:91], v[2:3]
	v_mov_b64_e32 v[94:95], v[2:3]
	v_mov_b64_e32 v[106:107], v[2:3]
	v_mov_b64_e32 v[110:111], v[2:3]
	v_mov_b64_e32 v[122:123], v[2:3]
	v_mov_b64_e32 v[126:127], v[2:3]
	s_barrier
